# c3 + prologue x->bf16 copy loop with 4 loads in flight per thread
# speedup vs baseline: 1.0168x; 1.0018x over previous
; __device__ __forceinline__ int opaque_tid() { int t = threadIdx.x; asm volatile("" : "+v"(t)); return t; }
; __device__ __forceinline__ unsigned cvtpk(float lo, float hi) { return __builtin_bit_cast(unsigned, __builtin_convertvector(f32x2_cv{lo, hi}, bf16x2_cv)); }
; __device__ __forceinline__ void convert_rows_bf16(const float* __restrict__ src, bf16_t* __restrict__ dst, size_t n) {
;     const int tid_ = opaque_tid();
;     const size_t n4 = n / 4;
;     for (size_t i = (size_t)blockIdx.x * NTHR + tid_; i < n4; i += (size_t)NBLK * NTHR) {
;         const float4 v = ((const float4*)src)[i];
;         ((uint2*)dst)[i] = make_uint2(cvtpk(v.x, v.y), cvtpk(v.z, v.w));
;     }
; }
.LBB0_11:
	v_lshl_add_u64 v[14:15], v[6:7], 0, s[12:13]
	v_lshl_add_u64 v[16:17], v[14:15], 0, s[12:13]
	v_lshl_add_u64 v[18:19], v[16:17], 0, s[12:13]
	global_load_dwordx4 v[8:11], v[6:7], off
	global_load_dwordx4 v[20:23], v[14:15], off
	global_load_dwordx4 v[24:27], v[16:17], off
	global_load_dwordx4 v[28:31], v[18:19], off
	v_add_co_u32_e32 v12, vcc, -4, v4
	s_nop 1
	v_addc_co_u32_e32 v13, vcc, -1, v5, vcc
	v_lshl_add_u64 v[32:33], v[12:13], 0, s[10:11]
	v_lshl_add_u64 v[34:35], v[32:33], 0, s[10:11]
	v_lshl_add_u64 v[36:37], v[34:35], 0, s[10:11]
	v_lshl_add_u64 v[2:3], v[2:3], 0, s[8:9]
	v_lshl_add_u64 v[2:3], v[2:3], 0, s[8:9]
	v_lshl_add_u64 v[2:3], v[2:3], 0, s[8:9]
	v_lshl_add_u64 v[2:3], v[2:3], 0, s[8:9]
	v_cmp_lt_u64_e32 vcc, s[14:15], v[2:3]
	v_lshl_add_u64 v[4:5], v[4:5], 0, s[10:11]
	v_lshl_add_u64 v[4:5], v[4:5], 0, s[10:11]
	v_lshl_add_u64 v[4:5], v[4:5], 0, s[10:11]
	v_lshl_add_u64 v[4:5], v[4:5], 0, s[10:11]
	v_lshl_add_u64 v[6:7], v[18:19], 0, s[12:13]
	s_or_b64 s[6:7], vcc, s[6:7]
	s_waitcnt vmcnt(3)
	v_cvt_pk_bf16_f32 v38, v8, v9
	v_cvt_pk_bf16_f32 v39, v10, v11
	global_store_dwordx2 v[12:13], v[38:39], off
	s_waitcnt vmcnt(3)
	v_cvt_pk_bf16_f32 v40, v20, v21
	v_cvt_pk_bf16_f32 v41, v22, v23
	global_store_dwordx2 v[32:33], v[40:41], off
	s_waitcnt vmcnt(3)
	v_cvt_pk_bf16_f32 v38, v24, v25
	v_cvt_pk_bf16_f32 v39, v26, v27
	global_store_dwordx2 v[34:35], v[38:39], off
	s_waitcnt vmcnt(3)
	v_cvt_pk_bf16_f32 v40, v28, v29
	v_cvt_pk_bf16_f32 v41, v30, v31
	global_store_dwordx2 v[36:37], v[40:41], off
	s_andn2_b64 exec, exec, s[6:7]
	s_cbranch_execnz .LBB0_11
